# MIX dispatch remap (sample-chain CU partners start with attention, prompt chains on the other CUs) + 3-step-deep LDS prefetch in sample chain
# speedup vs baseline: 1.0205x; 1.0205x over previous
.LBB0_1136:
	s_andn2_b64 vcc, exec, s[0:1]
	s_cbranch_vccnz .LBB0_1017
	v_readlane_b32 s2, v207, 49
	v_readlane_b32 s3, v207, 50
	s_mov_b64 s[0:1], -1
	s_and_b64 vcc, exec, s[2:3]
	s_cbranch_vccz .LBB0_1233
	v_readlane_b32 s0, v207, 52
	v_readlane_b32 s1, v207, 53
	s_andn2_b64 vcc, exec, s[0:1]
	v_readlane_b32 s51, v209, 0
	s_nop 3
	s_add_i32 s0, s51, 0x80
	s_sub_i32 s2, s51, 0x80
	s_cmpk_lt_u32 s51, 0x180
	s_cselect_b32 s0, s0, s2
	s_cmpk_lt_u32 s51, 0x100
	s_cselect_b32 s51, s51, s0
	s_mov_b32 s85, s51
	s_lshl_b32 s0, s51, 5
	v_writelane_b32 v206, s0, 51
	s_lshl_b32 s0, s51, 6
	s_add_i32 s0, s0, 0xffff5600
	v_writelane_b32 v205, s0, 31
	s_lshl_b32 s31, s51, 4
	s_addk_i32 s31, 0xc580
	s_add_i32 s30, s51, 0xfffffb58
	s_lshl_b32 s0, s51, 4
	s_add_i32 s0, s0, 0xffffb580
	v_writelane_b32 v205, s0, 29
	s_cbranch_vccz .LBB0_1152

.LBB0_1251:
	ds_read_b128 v[156:159], v90 offset:0
	ds_read_b128 v[160:163], v90 offset:256
	ds_read_b128 v[168:171], v90 offset:768
	ds_read_b32 v176, v103 offset:1280
	ds_read_b128 v[164:167], v90 offset:512
	ds_read_b128 v[172:175], v90 offset:1024
	ds_read_b128 v[180:183], v90 offset:1536
	ds_read_b128 v[184:187], v90 offset:1792
	ds_read_b128 v[192:195], v90 offset:2304
	ds_read_b32 v178, v103 offset:2816
	ds_read_b128 v[188:191], v90 offset:2048
	ds_read_b128 v[196:199], v90 offset:2560
	ds_read_b128 v[52:55], v90 offset:3072
	ds_read_b128 v[56:59], v90 offset:3328
	ds_read_b128 v[64:67], v90 offset:3840
	ds_read_b32 v200, v103 offset:4352
	ds_read_b128 v[60:63], v90 offset:3584
	ds_read_b128 v[68:71], v90 offset:4096
	s_waitcnt lgkmcnt(12)
	v_pk_mul_f32 v[72:73], v[44:45], v[158:159]
	v_pk_mul_f32 v[74:75], v[42:43], v[160:161]
	v_pk_fma_f32 v[72:73], v[42:43], v[156:157], v[72:73]
	v_pk_mul_f32 v[76:77], v[44:45], v[162:163]
	v_add_f32_e32 v78, v72, v73
	v_pk_fma_f32 v[74:75], v[176:177], v[168:169], v[74:75] op_sel_hi:[0,1,1]
	v_pk_fma_f32 v[76:77], v[176:177], v[170:171], v[76:77] op_sel_hi:[0,1,1]
	v_add_f32_dpp v78, v78, v78 quad_perm:[1,0,3,2] row_mask:0xf bank_mask:0xf bound_ctrl:1
	ds_read_b128 v[210:213], v90 offset:4608
	ds_read_b128 v[214:217], v90 offset:4864
	v_add_f32_dpp v78, v78, v78 quad_perm:[2,3,0,1] row_mask:0xf bank_mask:0xf bound_ctrl:1
	ds_read_b128 v[222:225], v90 offset:5376
	ds_read_b32 v230, v103 offset:5888
	v_add_f32_dpp v78, v78, v78 row_half_mirror row_mask:0xf bank_mask:0xf bound_ctrl:1
	ds_read_b128 v[218:221], v90 offset:5120
	ds_read_b128 v[226:229], v90 offset:5632
	v_add_f32_dpp v78, v78, v78 row_mirror row_mask:0xf bank_mask:0xf bound_ctrl:1
	v_pk_fma_f32 v[44:45], v[166:167], v[78:79], v[76:77] op_sel_hi:[1,0,1]
	v_pk_fma_f32 v[42:43], v[164:165], v[78:79], v[74:75] op_sel_hi:[1,0,1]
	s_waitcnt lgkmcnt(12)
	v_pk_mul_f32 v[72:73], v[44:45], v[182:183]
	v_pk_mul_f32 v[80:81], v[44:45], v[174:175]
	v_pk_fma_f32 v[72:73], v[42:43], v[180:181], v[72:73]
	v_pk_fma_f32 v[80:81], v[42:43], v[172:173], v[80:81]
	v_add_f32_e32 v78, v72, v73
	v_add_f32_e32 v46, v80, v81
	v_pk_mul_f32 v[74:75], v[42:43], v[184:185]
	v_add_f32_dpp v78, v78, v78 quad_perm:[1,0,3,2] row_mask:0xf bank_mask:0xf bound_ctrl:1
	v_pk_mul_f32 v[76:77], v[44:45], v[186:187]
	v_pk_fma_f32 v[74:75], v[178:179], v[192:193], v[74:75] op_sel_hi:[0,1,1]
	v_add_f32_dpp v78, v78, v78 quad_perm:[2,3,0,1] row_mask:0xf bank_mask:0xf bound_ctrl:1
	v_pk_fma_f32 v[76:77], v[178:179], v[194:195], v[76:77] op_sel_hi:[0,1,1]
	ds_read_b128 v[156:159], v90 offset:6144
	v_add_f32_dpp v78, v78, v78 row_half_mirror row_mask:0xf bank_mask:0xf bound_ctrl:1
	ds_read_b128 v[160:163], v90 offset:6400
	ds_read_b128 v[168:171], v90 offset:6912
	v_add_f32_dpp v78, v78, v78 row_mirror row_mask:0xf bank_mask:0xf bound_ctrl:1
	v_pk_fma_f32 v[44:45], v[190:191], v[78:79], v[76:77] op_sel_hi:[1,0,1]
	v_pk_fma_f32 v[42:43], v[188:189], v[78:79], v[74:75] op_sel_hi:[1,0,1]
	ds_read_b32 v176, v103 offset:7424
	ds_read_b128 v[164:167], v90 offset:6656
	ds_read_b128 v[172:175], v90 offset:7168
	s_waitcnt lgkmcnt(12)
	v_pk_mul_f32 v[72:73], v[44:45], v[54:55]
	v_pk_mul_f32 v[80:81], v[44:45], v[198:199]
	v_pk_fma_f32 v[72:73], v[42:43], v[52:53], v[72:73]
	v_pk_fma_f32 v[80:81], v[42:43], v[196:197], v[80:81]
	v_add_f32_e32 v78, v72, v73
	v_add_f32_e32 v47, v80, v81
	v_pk_mul_f32 v[74:75], v[42:43], v[56:57]
	v_add_f32_dpp v78, v78, v78 quad_perm:[1,0,3,2] row_mask:0xf bank_mask:0xf bound_ctrl:1
	v_pk_mul_f32 v[76:77], v[44:45], v[58:59]
	v_pk_fma_f32 v[74:75], v[200:201], v[64:65], v[74:75] op_sel_hi:[0,1,1]
	v_add_f32_dpp v78, v78, v78 quad_perm:[2,3,0,1] row_mask:0xf bank_mask:0xf bound_ctrl:1
	v_pk_fma_f32 v[76:77], v[200:201], v[66:67], v[76:77] op_sel_hi:[0,1,1]
	ds_read_b128 v[180:183], v90 offset:7680
	v_add_f32_dpp v78, v78, v78 row_half_mirror row_mask:0xf bank_mask:0xf bound_ctrl:1
	ds_read_b128 v[184:187], v90 offset:7936
	ds_read_b128 v[192:195], v90 offset:8448
	v_add_f32_dpp v78, v78, v78 row_mirror row_mask:0xf bank_mask:0xf bound_ctrl:1
	v_pk_fma_f32 v[44:45], v[62:63], v[78:79], v[76:77] op_sel_hi:[1,0,1]
	v_pk_fma_f32 v[42:43], v[60:61], v[78:79], v[74:75] op_sel_hi:[1,0,1]
	ds_read_b32 v178, v103 offset:8960
	ds_read_b128 v[188:191], v90 offset:8192
	ds_read_b128 v[196:199], v90 offset:8704
	s_waitcnt lgkmcnt(12)
	v_pk_mul_f32 v[72:73], v[44:45], v[212:213]
	v_pk_mul_f32 v[80:81], v[44:45], v[70:71]
	v_pk_fma_f32 v[72:73], v[42:43], v[210:211], v[72:73]
	v_pk_fma_f32 v[80:81], v[42:43], v[68:69], v[80:81]
	v_add_f32_e32 v78, v72, v73
	v_add_f32_e32 v48, v80, v81
	v_pk_mul_f32 v[74:75], v[42:43], v[214:215]
	v_add_f32_dpp v78, v78, v78 quad_perm:[1,0,3,2] row_mask:0xf bank_mask:0xf bound_ctrl:1
	v_pk_mul_f32 v[76:77], v[44:45], v[216:217]
	v_pk_fma_f32 v[74:75], v[230:231], v[222:223], v[74:75] op_sel_hi:[0,1,1]
	v_add_f32_dpp v78, v78, v78 quad_perm:[2,3,0,1] row_mask:0xf bank_mask:0xf bound_ctrl:1
	v_pk_fma_f32 v[76:77], v[230:231], v[224:225], v[76:77] op_sel_hi:[0,1,1]
	ds_read_b128 v[52:55], v90 offset:9216
	v_add_f32_dpp v78, v78, v78 row_half_mirror row_mask:0xf bank_mask:0xf bound_ctrl:1
	ds_read_b128 v[56:59], v90 offset:9472
	ds_read_b128 v[64:67], v90 offset:9984
	v_add_f32_dpp v78, v78, v78 row_mirror row_mask:0xf bank_mask:0xf bound_ctrl:1
	v_pk_fma_f32 v[44:45], v[220:221], v[78:79], v[76:77] op_sel_hi:[1,0,1]
	v_pk_fma_f32 v[42:43], v[218:219], v[78:79], v[74:75] op_sel_hi:[1,0,1]
	ds_read_b32 v200, v103 offset:10496
	ds_read_b128 v[60:63], v90 offset:9728
	ds_read_b128 v[68:71], v90 offset:10240
	s_waitcnt lgkmcnt(12)
	v_pk_mul_f32 v[72:73], v[44:45], v[158:159]
	v_pk_mul_f32 v[80:81], v[44:45], v[228:229]
	v_pk_fma_f32 v[72:73], v[42:43], v[156:157], v[72:73]
	v_pk_fma_f32 v[80:81], v[42:43], v[226:227], v[80:81]
	v_add_f32_e32 v78, v72, v73
	v_add_f32_e32 v49, v80, v81
	v_pk_mul_f32 v[74:75], v[42:43], v[160:161]
	v_add_f32_dpp v78, v78, v78 quad_perm:[1,0,3,2] row_mask:0xf bank_mask:0xf bound_ctrl:1
	v_pk_mul_f32 v[76:77], v[44:45], v[162:163]
	v_pk_fma_f32 v[74:75], v[176:177], v[168:169], v[74:75] op_sel_hi:[0,1,1]
	v_add_f32_dpp v78, v78, v78 quad_perm:[2,3,0,1] row_mask:0xf bank_mask:0xf bound_ctrl:1
	v_pk_fma_f32 v[76:77], v[176:177], v[170:171], v[76:77] op_sel_hi:[0,1,1]
	ds_read_b128 v[210:213], v90 offset:10752
	v_add_f32_dpp v78, v78, v78 row_half_mirror row_mask:0xf bank_mask:0xf bound_ctrl:1
	ds_read_b128 v[214:217], v90 offset:11008
	ds_read_b128 v[222:225], v90 offset:11520
	v_add_f32_dpp v78, v78, v78 row_mirror row_mask:0xf bank_mask:0xf bound_ctrl:1
	v_pk_fma_f32 v[44:45], v[166:167], v[78:79], v[76:77] op_sel_hi:[1,0,1]
	v_pk_fma_f32 v[42:43], v[164:165], v[78:79], v[74:75] op_sel_hi:[1,0,1]
	ds_read_b32 v230, v103 offset:12032
	ds_read_b128 v[218:221], v90 offset:11264
	ds_read_b128 v[226:229], v90 offset:11776
	s_waitcnt lgkmcnt(12)
	v_pk_mul_f32 v[72:73], v[44:45], v[182:183]
	v_pk_mul_f32 v[80:81], v[44:45], v[174:175]
	v_pk_fma_f32 v[72:73], v[42:43], v[180:181], v[72:73]
	v_pk_fma_f32 v[80:81], v[42:43], v[172:173], v[80:81]
	v_add_f32_e32 v78, v72, v73
	v_add_f32_e32 v50, v80, v81
	v_pk_mul_f32 v[74:75], v[42:43], v[184:185]
	v_add_f32_dpp v78, v78, v78 quad_perm:[1,0,3,2] row_mask:0xf bank_mask:0xf bound_ctrl:1
	v_pk_mul_f32 v[76:77], v[44:45], v[186:187]
	v_pk_fma_f32 v[74:75], v[178:179], v[192:193], v[74:75] op_sel_hi:[0,1,1]
	v_add_f32_dpp v78, v78, v78 quad_perm:[2,3,0,1] row_mask:0xf bank_mask:0xf bound_ctrl:1
	v_pk_fma_f32 v[76:77], v[178:179], v[194:195], v[76:77] op_sel_hi:[0,1,1]
	ds_read_b128 v[156:159], v90 offset:12288
	v_add_f32_dpp v78, v78, v78 row_half_mirror row_mask:0xf bank_mask:0xf bound_ctrl:1
	ds_read_b128 v[160:163], v90 offset:12544
	ds_read_b128 v[168:171], v90 offset:13056
	v_add_f32_dpp v78, v78, v78 row_mirror row_mask:0xf bank_mask:0xf bound_ctrl:1
	v_pk_fma_f32 v[44:45], v[190:191], v[78:79], v[76:77] op_sel_hi:[1,0,1]
	v_pk_fma_f32 v[42:43], v[188:189], v[78:79], v[74:75] op_sel_hi:[1,0,1]
	ds_read_b32 v176, v103 offset:13568
	ds_read_b128 v[164:167], v90 offset:12800
	ds_read_b128 v[172:175], v90 offset:13312
	s_waitcnt lgkmcnt(12)
	v_pk_mul_f32 v[72:73], v[44:45], v[54:55]
	v_pk_mul_f32 v[80:81], v[44:45], v[198:199]
	v_pk_fma_f32 v[72:73], v[42:43], v[52:53], v[72:73]
	v_pk_fma_f32 v[80:81], v[42:43], v[196:197], v[80:81]
	v_add_f32_e32 v78, v72, v73
	v_add_f32_e32 v51, v80, v81
	v_pk_mul_f32 v[74:75], v[42:43], v[56:57]
	v_add_f32_dpp v78, v78, v78 quad_perm:[1,0,3,2] row_mask:0xf bank_mask:0xf bound_ctrl:1
	v_pk_mul_f32 v[76:77], v[44:45], v[58:59]
	v_pk_fma_f32 v[74:75], v[200:201], v[64:65], v[74:75] op_sel_hi:[0,1,1]
	v_add_f32_dpp v78, v78, v78 quad_perm:[2,3,0,1] row_mask:0xf bank_mask:0xf bound_ctrl:1
	v_pk_fma_f32 v[76:77], v[200:201], v[66:67], v[76:77] op_sel_hi:[0,1,1]
	ds_read_b128 v[180:183], v90 offset:13824
	v_add_f32_dpp v78, v78, v78 row_half_mirror row_mask:0xf bank_mask:0xf bound_ctrl:1
	ds_read_b128 v[184:187], v90 offset:14080
	ds_read_b128 v[192:195], v90 offset:14592
	v_add_f32_dpp v78, v78, v78 row_mirror row_mask:0xf bank_mask:0xf bound_ctrl:1
	v_pk_fma_f32 v[44:45], v[62:63], v[78:79], v[76:77] op_sel_hi:[1,0,1]
	v_pk_fma_f32 v[42:43], v[60:61], v[78:79], v[74:75] op_sel_hi:[1,0,1]
	ds_read_b32 v178, v103 offset:15104
	ds_read_b128 v[188:191], v90 offset:14336
	ds_read_b128 v[196:199], v90 offset:14848
	s_waitcnt lgkmcnt(12)
	v_pk_mul_f32 v[72:73], v[44:45], v[212:213]
	v_pk_mul_f32 v[80:81], v[44:45], v[70:71]
	v_pk_fma_f32 v[72:73], v[42:43], v[210:211], v[72:73]
	v_pk_fma_f32 v[80:81], v[42:43], v[68:69], v[80:81]
	v_add_f32_e32 v78, v72, v73
	v_add_f32_e32 v82, v80, v81
	v_pk_mul_f32 v[74:75], v[42:43], v[214:215]
	v_add_f32_dpp v78, v78, v78 quad_perm:[1,0,3,2] row_mask:0xf bank_mask:0xf bound_ctrl:1
	v_pk_mul_f32 v[76:77], v[44:45], v[216:217]
	v_pk_fma_f32 v[74:75], v[230:231], v[222:223], v[74:75] op_sel_hi:[0,1,1]
	v_add_f32_dpp v78, v78, v78 quad_perm:[2,3,0,1] row_mask:0xf bank_mask:0xf bound_ctrl:1
	v_pk_fma_f32 v[76:77], v[230:231], v[224:225], v[76:77] op_sel_hi:[0,1,1]
	ds_read_b128 v[52:55], v90 offset:15360
	v_add_f32_dpp v78, v78, v78 row_half_mirror row_mask:0xf bank_mask:0xf bound_ctrl:1
	ds_read_b128 v[56:59], v90 offset:15616
	ds_read_b128 v[64:67], v90 offset:16128
	v_add_f32_dpp v78, v78, v78 row_mirror row_mask:0xf bank_mask:0xf bound_ctrl:1
	v_pk_fma_f32 v[44:45], v[220:221], v[78:79], v[76:77] op_sel_hi:[1,0,1]
	v_pk_fma_f32 v[42:43], v[218:219], v[78:79], v[74:75] op_sel_hi:[1,0,1]
	ds_read_b32 v200, v103 offset:16640
	ds_read_b128 v[60:63], v90 offset:15872
	ds_read_b128 v[68:71], v90 offset:16384
	s_waitcnt lgkmcnt(12)
	v_pk_mul_f32 v[72:73], v[44:45], v[158:159]
	v_pk_mul_f32 v[80:81], v[44:45], v[228:229]
	v_pk_fma_f32 v[72:73], v[42:43], v[156:157], v[72:73]
	v_pk_fma_f32 v[80:81], v[42:43], v[226:227], v[80:81]
	v_add_f32_e32 v78, v72, v73
	v_add_f32_e32 v83, v80, v81
	v_pk_mul_f32 v[74:75], v[42:43], v[160:161]
	v_add_f32_dpp v78, v78, v78 quad_perm:[1,0,3,2] row_mask:0xf bank_mask:0xf bound_ctrl:1
	v_pk_mul_f32 v[76:77], v[44:45], v[162:163]
	v_pk_fma_f32 v[74:75], v[176:177], v[168:169], v[74:75] op_sel_hi:[0,1,1]
	v_add_f32_dpp v78, v78, v78 quad_perm:[2,3,0,1] row_mask:0xf bank_mask:0xf bound_ctrl:1
	v_pk_fma_f32 v[76:77], v[176:177], v[170:171], v[76:77] op_sel_hi:[0,1,1]
	ds_read_b128 v[210:213], v90 offset:16896
	v_add_f32_dpp v78, v78, v78 row_half_mirror row_mask:0xf bank_mask:0xf bound_ctrl:1
	ds_read_b128 v[214:217], v90 offset:17152
	ds_read_b128 v[222:225], v90 offset:17664
	v_add_f32_dpp v78, v78, v78 row_mirror row_mask:0xf bank_mask:0xf bound_ctrl:1
	v_pk_fma_f32 v[44:45], v[166:167], v[78:79], v[76:77] op_sel_hi:[1,0,1]
	v_pk_fma_f32 v[42:43], v[164:165], v[78:79], v[74:75] op_sel_hi:[1,0,1]
	ds_read_b32 v230, v103 offset:18176
	ds_read_b128 v[218:221], v90 offset:17408
	ds_read_b128 v[226:229], v90 offset:17920
	s_waitcnt lgkmcnt(12)
	v_pk_mul_f32 v[72:73], v[44:45], v[182:183]
	v_pk_mul_f32 v[80:81], v[44:45], v[174:175]
	v_pk_fma_f32 v[72:73], v[42:43], v[180:181], v[72:73]
	v_pk_fma_f32 v[80:81], v[42:43], v[172:173], v[80:81]
	v_add_f32_e32 v78, v72, v73
	v_add_f32_e32 v84, v80, v81
	v_pk_mul_f32 v[74:75], v[42:43], v[184:185]
	v_add_f32_dpp v78, v78, v78 quad_perm:[1,0,3,2] row_mask:0xf bank_mask:0xf bound_ctrl:1
	v_pk_mul_f32 v[76:77], v[44:45], v[186:187]
	v_pk_fma_f32 v[74:75], v[178:179], v[192:193], v[74:75] op_sel_hi:[0,1,1]
	v_add_f32_dpp v78, v78, v78 quad_perm:[2,3,0,1] row_mask:0xf bank_mask:0xf bound_ctrl:1
	v_pk_fma_f32 v[76:77], v[178:179], v[194:195], v[76:77] op_sel_hi:[0,1,1]
	ds_read_b128 v[156:159], v90 offset:18432
	v_add_f32_dpp v78, v78, v78 row_half_mirror row_mask:0xf bank_mask:0xf bound_ctrl:1
	ds_read_b128 v[160:163], v90 offset:18688
	ds_read_b128 v[168:171], v90 offset:19200
	v_add_f32_dpp v78, v78, v78 row_mirror row_mask:0xf bank_mask:0xf bound_ctrl:1
	v_pk_fma_f32 v[44:45], v[190:191], v[78:79], v[76:77] op_sel_hi:[1,0,1]
	v_pk_fma_f32 v[42:43], v[188:189], v[78:79], v[74:75] op_sel_hi:[1,0,1]
	ds_read_b32 v176, v103 offset:19712
	ds_read_b128 v[164:167], v90 offset:18944
	ds_read_b128 v[172:175], v90 offset:19456
	s_waitcnt lgkmcnt(12)
	v_pk_mul_f32 v[72:73], v[44:45], v[54:55]
	v_pk_mul_f32 v[80:81], v[44:45], v[198:199]
	v_pk_fma_f32 v[72:73], v[42:43], v[52:53], v[72:73]
	v_pk_fma_f32 v[80:81], v[42:43], v[196:197], v[80:81]
	v_add_f32_e32 v78, v72, v73
	v_add_f32_e32 v85, v80, v81
	v_pk_mul_f32 v[74:75], v[42:43], v[56:57]
	v_add_f32_dpp v78, v78, v78 quad_perm:[1,0,3,2] row_mask:0xf bank_mask:0xf bound_ctrl:1
	v_pk_mul_f32 v[76:77], v[44:45], v[58:59]
	v_pk_fma_f32 v[74:75], v[200:201], v[64:65], v[74:75] op_sel_hi:[0,1,1]
	v_add_f32_dpp v78, v78, v78 quad_perm:[2,3,0,1] row_mask:0xf bank_mask:0xf bound_ctrl:1
	v_pk_fma_f32 v[76:77], v[200:201], v[66:67], v[76:77] op_sel_hi:[0,1,1]
	ds_read_b128 v[180:183], v90 offset:19968
	v_add_f32_dpp v78, v78, v78 row_half_mirror row_mask:0xf bank_mask:0xf bound_ctrl:1
	ds_read_b128 v[184:187], v90 offset:20224
	ds_read_b128 v[192:195], v90 offset:20736
	v_add_f32_dpp v78, v78, v78 row_mirror row_mask:0xf bank_mask:0xf bound_ctrl:1
	v_pk_fma_f32 v[44:45], v[62:63], v[78:79], v[76:77] op_sel_hi:[1,0,1]
	v_pk_fma_f32 v[42:43], v[60:61], v[78:79], v[74:75] op_sel_hi:[1,0,1]
	ds_read_b32 v178, v103 offset:21248
	ds_read_b128 v[188:191], v90 offset:20480
	ds_read_b128 v[196:199], v90 offset:20992
	s_waitcnt lgkmcnt(12)
	v_pk_mul_f32 v[72:73], v[44:45], v[212:213]
	v_pk_mul_f32 v[80:81], v[44:45], v[70:71]
	v_pk_fma_f32 v[72:73], v[42:43], v[210:211], v[72:73]
	v_pk_fma_f32 v[80:81], v[42:43], v[68:69], v[80:81]
	v_add_f32_e32 v78, v72, v73
	v_add_f32_e32 v100, v80, v81
	v_pk_mul_f32 v[74:75], v[42:43], v[214:215]
	v_add_f32_dpp v78, v78, v78 quad_perm:[1,0,3,2] row_mask:0xf bank_mask:0xf bound_ctrl:1
	v_pk_mul_f32 v[76:77], v[44:45], v[216:217]
	v_pk_fma_f32 v[74:75], v[230:231], v[222:223], v[74:75] op_sel_hi:[0,1,1]
	v_add_f32_dpp v78, v78, v78 quad_perm:[2,3,0,1] row_mask:0xf bank_mask:0xf bound_ctrl:1
	v_pk_fma_f32 v[76:77], v[230:231], v[224:225], v[76:77] op_sel_hi:[0,1,1]
	ds_read_b128 v[52:55], v90 offset:21504
	v_add_f32_dpp v78, v78, v78 row_half_mirror row_mask:0xf bank_mask:0xf bound_ctrl:1
	ds_read_b128 v[56:59], v90 offset:21760
	ds_read_b128 v[64:67], v90 offset:22272
	v_add_f32_dpp v78, v78, v78 row_mirror row_mask:0xf bank_mask:0xf bound_ctrl:1
	v_pk_fma_f32 v[44:45], v[220:221], v[78:79], v[76:77] op_sel_hi:[1,0,1]
	v_pk_fma_f32 v[42:43], v[218:219], v[78:79], v[74:75] op_sel_hi:[1,0,1]
	ds_read_b32 v200, v103 offset:22784
	ds_read_b128 v[60:63], v90 offset:22016
	ds_read_b128 v[68:71], v90 offset:22528
	s_waitcnt lgkmcnt(12)
	v_pk_mul_f32 v[72:73], v[44:45], v[158:159]
	v_pk_mul_f32 v[80:81], v[44:45], v[228:229]
	v_pk_fma_f32 v[72:73], v[42:43], v[156:157], v[72:73]
	v_pk_fma_f32 v[80:81], v[42:43], v[226:227], v[80:81]
	v_add_f32_e32 v78, v72, v73
	v_add_f32_e32 v101, v80, v81
	v_pk_mul_f32 v[74:75], v[42:43], v[160:161]
	v_add_f32_dpp v78, v78, v78 quad_perm:[1,0,3,2] row_mask:0xf bank_mask:0xf bound_ctrl:1
	v_pk_mul_f32 v[76:77], v[44:45], v[162:163]
	v_pk_fma_f32 v[74:75], v[176:177], v[168:169], v[74:75] op_sel_hi:[0,1,1]
	v_add_f32_dpp v78, v78, v78 quad_perm:[2,3,0,1] row_mask:0xf bank_mask:0xf bound_ctrl:1
	v_pk_fma_f32 v[76:77], v[176:177], v[170:171], v[76:77] op_sel_hi:[0,1,1]
	ds_read_b128 v[210:213], v90 offset:23040
	v_add_f32_dpp v78, v78, v78 row_half_mirror row_mask:0xf bank_mask:0xf bound_ctrl:1
	ds_read_b128 v[214:217], v90 offset:23296
	ds_read_b128 v[222:225], v90 offset:23808
	v_add_f32_dpp v78, v78, v78 row_mirror row_mask:0xf bank_mask:0xf bound_ctrl:1
	v_pk_fma_f32 v[44:45], v[166:167], v[78:79], v[76:77] op_sel_hi:[1,0,1]
	v_pk_fma_f32 v[42:43], v[164:165], v[78:79], v[74:75] op_sel_hi:[1,0,1]
	ds_read_b32 v230, v103 offset:24320
	ds_read_b128 v[218:221], v90 offset:23552
	ds_read_b128 v[226:229], v90 offset:24064
	s_waitcnt lgkmcnt(12)
	v_pk_mul_f32 v[72:73], v[44:45], v[182:183]
	v_pk_mul_f32 v[80:81], v[44:45], v[174:175]
	v_pk_fma_f32 v[72:73], v[42:43], v[180:181], v[72:73]
	v_pk_fma_f32 v[80:81], v[42:43], v[172:173], v[80:81]
	v_add_f32_e32 v78, v72, v73
	v_add_f32_e32 v102, v80, v81
	v_pk_mul_f32 v[74:75], v[42:43], v[184:185]
	v_add_f32_dpp v78, v78, v78 quad_perm:[1,0,3,2] row_mask:0xf bank_mask:0xf bound_ctrl:1
	v_pk_mul_f32 v[76:77], v[44:45], v[186:187]
	v_pk_fma_f32 v[74:75], v[178:179], v[192:193], v[74:75] op_sel_hi:[0,1,1]
	v_add_f32_dpp v78, v78, v78 quad_perm:[2,3,0,1] row_mask:0xf bank_mask:0xf bound_ctrl:1
	v_pk_fma_f32 v[76:77], v[178:179], v[194:195], v[76:77] op_sel_hi:[0,1,1]
	s_nop 0
	v_add_f32_dpp v78, v78, v78 row_half_mirror row_mask:0xf bank_mask:0xf bound_ctrl:1
	s_nop 0
	s_nop 0
	v_add_f32_dpp v78, v78, v78 row_mirror row_mask:0xf bank_mask:0xf bound_ctrl:1
	v_pk_fma_f32 v[44:45], v[190:191], v[78:79], v[76:77] op_sel_hi:[1,0,1]
	v_pk_fma_f32 v[42:43], v[188:189], v[78:79], v[74:75] op_sel_hi:[1,0,1]
	s_waitcnt lgkmcnt(6)
	v_pk_mul_f32 v[72:73], v[44:45], v[54:55]
	v_pk_mul_f32 v[80:81], v[44:45], v[198:199]
	v_pk_fma_f32 v[72:73], v[42:43], v[52:53], v[72:73]
	v_pk_fma_f32 v[80:81], v[42:43], v[196:197], v[80:81]
	v_add_f32_e32 v78, v72, v73
	v_add_f32_e32 v104, v80, v81
	v_pk_mul_f32 v[74:75], v[42:43], v[56:57]
	v_add_f32_dpp v78, v78, v78 quad_perm:[1,0,3,2] row_mask:0xf bank_mask:0xf bound_ctrl:1
	v_pk_mul_f32 v[76:77], v[44:45], v[58:59]
	v_pk_fma_f32 v[74:75], v[200:201], v[64:65], v[74:75] op_sel_hi:[0,1,1]
	v_add_f32_dpp v78, v78, v78 quad_perm:[2,3,0,1] row_mask:0xf bank_mask:0xf bound_ctrl:1
	v_pk_fma_f32 v[76:77], v[200:201], v[66:67], v[76:77] op_sel_hi:[0,1,1]
	s_nop 0
	v_add_f32_dpp v78, v78, v78 row_half_mirror row_mask:0xf bank_mask:0xf bound_ctrl:1
	s_nop 0
	s_nop 0
	v_add_f32_dpp v78, v78, v78 row_mirror row_mask:0xf bank_mask:0xf bound_ctrl:1
	v_pk_fma_f32 v[44:45], v[62:63], v[78:79], v[76:77] op_sel_hi:[1,0,1]
	v_pk_fma_f32 v[42:43], v[60:61], v[78:79], v[74:75] op_sel_hi:[1,0,1]
	s_waitcnt lgkmcnt(0)
	v_pk_mul_f32 v[72:73], v[44:45], v[212:213]
	v_pk_mul_f32 v[80:81], v[44:45], v[70:71]
	v_pk_fma_f32 v[72:73], v[42:43], v[210:211], v[72:73]
	v_pk_fma_f32 v[80:81], v[42:43], v[68:69], v[80:81]
	v_add_f32_e32 v78, v72, v73
	v_add_f32_e32 v108, v80, v81
	v_pk_mul_f32 v[74:75], v[42:43], v[214:215]
	v_add_f32_dpp v78, v78, v78 quad_perm:[1,0,3,2] row_mask:0xf bank_mask:0xf bound_ctrl:1
	v_pk_mul_f32 v[76:77], v[44:45], v[216:217]
	v_pk_fma_f32 v[74:75], v[230:231], v[222:223], v[74:75] op_sel_hi:[0,1,1]
	v_add_f32_dpp v78, v78, v78 quad_perm:[2,3,0,1] row_mask:0xf bank_mask:0xf bound_ctrl:1
	v_pk_fma_f32 v[76:77], v[230:231], v[224:225], v[76:77] op_sel_hi:[0,1,1]
	s_nop 0
	v_add_f32_dpp v78, v78, v78 row_half_mirror row_mask:0xf bank_mask:0xf bound_ctrl:1
	s_nop 0
	s_nop 0
	v_add_f32_dpp v78, v78, v78 row_mirror row_mask:0xf bank_mask:0xf bound_ctrl:1
	v_pk_fma_f32 v[44:45], v[220:221], v[78:79], v[76:77] op_sel_hi:[1,0,1]
	v_pk_fma_f32 v[42:43], v[218:219], v[78:79], v[74:75] op_sel_hi:[1,0,1]
	s_mov_b32 s4, 0xcccccccc
	v_pk_mul_f32 v[80:81], v[44:45], v[228:229]
	s_mov_b32 s5, 0xcccccccc
	v_pk_fma_f32 v[80:81], v[42:43], v[226:227], v[80:81]
	s_mov_b32 s12, 0xaaaaaaaa
	s_mov_b32 s13, 0xaaaaaaaa
	v_add_f32_e32 v177, v80, v81
	v_add_f32_dpp v46, v46, v46 row_ror:8 row_mask:0xf bank_mask:0x3
	v_add_f32_dpp v47, v47, v47 row_ror:8 row_mask:0xf bank_mask:0x3
	v_add_f32_dpp v48, v48, v48 row_ror:8 row_mask:0xf bank_mask:0x3
	v_add_f32_dpp v49, v49, v49 row_ror:8 row_mask:0xf bank_mask:0x3
	v_add_f32_dpp v50, v50, v50 row_ror:8 row_mask:0xf bank_mask:0x3
	v_add_f32_dpp v51, v51, v51 row_ror:8 row_mask:0xf bank_mask:0x3
	v_add_f32_dpp v82, v82, v82 row_ror:8 row_mask:0xf bank_mask:0x3
	v_add_f32_dpp v83, v83, v83 row_ror:8 row_mask:0xf bank_mask:0x3
	v_add_f32_dpp v46, v84, v84 row_ror:8 row_mask:0xf bank_mask:0xc
	v_add_f32_dpp v47, v85, v85 row_ror:8 row_mask:0xf bank_mask:0xc
	v_add_f32_dpp v48, v100, v100 row_ror:8 row_mask:0xf bank_mask:0xc
	v_add_f32_dpp v49, v101, v101 row_ror:8 row_mask:0xf bank_mask:0xc
	v_add_f32_dpp v50, v102, v102 row_ror:8 row_mask:0xf bank_mask:0xc
	v_add_f32_dpp v51, v104, v104 row_ror:8 row_mask:0xf bank_mask:0xc
	v_add_f32_dpp v82, v108, v108 row_ror:8 row_mask:0xf bank_mask:0xc
	v_add_f32_dpp v83, v177, v177 row_ror:8 row_mask:0xf bank_mask:0xc
	v_add_f32_dpp v46, v46, v46 row_shl:4 row_mask:0xf bank_mask:0x5
	v_add_f32_dpp v47, v47, v47 row_shl:4 row_mask:0xf bank_mask:0x5
	v_add_f32_dpp v48, v48, v48 row_shl:4 row_mask:0xf bank_mask:0x5
	v_add_f32_dpp v49, v49, v49 row_shl:4 row_mask:0xf bank_mask:0x5
	v_add_f32_dpp v46, v50, v50 row_shr:4 row_mask:0xf bank_mask:0xa
	v_add_f32_dpp v47, v51, v51 row_shr:4 row_mask:0xf bank_mask:0xa
	v_add_f32_dpp v48, v82, v82 row_shr:4 row_mask:0xf bank_mask:0xa
	v_add_f32_dpp v49, v83, v83 row_shr:4 row_mask:0xf bank_mask:0xa
	v_add_f32_dpp v84, v46, v46 quad_perm:[2,3,0,1] row_mask:0xf bank_mask:0xf
	v_add_f32_dpp v85, v47, v47 quad_perm:[2,3,0,1] row_mask:0xf bank_mask:0xf
	v_add_f32_dpp v100, v48, v48 quad_perm:[2,3,0,1] row_mask:0xf bank_mask:0xf
	v_add_f32_dpp v101, v49, v49 quad_perm:[2,3,0,1] row_mask:0xf bank_mask:0xf
	v_cndmask_b32_e64 v50, v84, v100, s[4:5]
	v_cndmask_b32_e64 v51, v85, v101, s[4:5]
	s_nop 0
	v_add_f32_dpp v82, v50, v50 quad_perm:[1,0,3,2] row_mask:0xf bank_mask:0xf
	v_add_f32_dpp v83, v51, v51 quad_perm:[1,0,3,2] row_mask:0xf bank_mask:0xf
	v_cndmask_b32_e64 v48, v82, v83, s[12:13]
	v_lshl_or_b32 v156, s7, 4, v87
	s_waitcnt vmcnt(1)
	v_and_b32_e32 v49, 0xffff0000, v27
	s_add_i32 s2, s7, 3
	s_cmp_ge_u32 s2, s19
	v_xad_u32 v46, v156, -1, s18
	v_cndmask_b32_e64 v46, v46, v156, s[16:17]
	v_ashrrev_i32_e32 v47, 31, v46
	v_lshlrev_b64 v[46:47], 10, v[46:47]
	v_lshl_add_u64 v[46:47], v[98:99], 0, v[46:47]
	global_store_dword v[46:47], v48, off
	v_lshlrev_b32_e32 v46, 16, v26
	v_and_b32_e32 v47, 0xffff0000, v26
	v_lshlrev_b32_e32 v48, 16, v27
	ds_write_b128 v96, v[2:5] offset:24576
	ds_write_b128 v96, v[6:9] offset:30720
	ds_write_b128 v96, v[10:13] offset:36864
	ds_write_b128 v96, v[14:17] offset:43008
	ds_write_b128 v97, v[46:49] offset:25600
	v_lshlrev_b32_e32 v46, 16, v28
	v_and_b32_e32 v47, 0xffff0000, v28
	v_lshlrev_b32_e32 v48, 16, v29
	v_and_b32_e32 v49, 0xffff0000, v29
	ds_write_b128 v97, v[46:49] offset:25616
	s_cbranch_scc1 .LBB0_1255
	s_lshl_b32 s2, s2, 4
	v_add_u32_e32 v12, s2, v1
	v_xad_u32 v2, v12, -1, s18
	v_sub_u32_e32 v13, s18, v12
	v_cndmask_b32_e64 v2, v2, v12, s[16:17]
	v_add_u32_e32 v4, 4, v12
	v_add_u32_e32 v5, -5, v13
	v_add_u32_e32 v10, 8, v12
	v_add_u32_e32 v11, -9, v13
	v_add_u32_e32 v12, 12, v12
	v_add_u32_e32 v13, -13, v13
	v_readlane_b32 s4, v206, 6
	v_cndmask_b32_e64 v4, v5, v4, s[16:17]
	v_cndmask_b32_e64 v10, v11, v10, s[16:17]
	v_cndmask_b32_e64 v12, v13, v12, s[16:17]
	v_add_u32_e32 v26, s2, v91
	v_add_u32_e32 v2, s4, v2
	v_add_u32_e32 v4, s4, v4
	v_add_u32_e32 v10, s4, v10
	v_add_u32_e32 v12, s4, v12
	v_xad_u32 v27, v26, -1, s18
	v_ashrrev_i32_e32 v3, 31, v2
	v_ashrrev_i32_e32 v5, 31, v4
	v_ashrrev_i32_e32 v11, 31, v10
	v_ashrrev_i32_e32 v13, 31, v12
	v_cndmask_b32_e64 v26, v27, v26, s[16:17]
	v_lshlrev_b64 v[2:3], 10, v[2:3]
	v_lshlrev_b64 v[4:5], 10, v[4:5]
	v_lshlrev_b64 v[10:11], 10, v[10:11]
	v_lshlrev_b64 v[12:13], 10, v[12:13]
	v_add_u32_e32 v26, s4, v26
	v_lshl_add_u64 v[2:3], v[92:93], 0, v[2:3]
	v_lshl_add_u64 v[6:7], v[92:93], 0, v[4:5]
	v_lshl_add_u64 v[10:11], v[92:93], 0, v[10:11]
	v_lshl_add_u64 v[14:15], v[92:93], 0, v[12:13]
	v_mad_i64_i32 v[26:27], s[2:3], v26, s37, v[94:95]
	global_load_dwordx4 v[2:5], v[2:3], off
	s_nop 0
	global_load_dwordx4 v[6:9], v[6:7], off
	s_nop 0
	global_load_dwordx4 v[10:13], v[10:11], off
	s_nop 0
	global_load_dwordx4 v[14:17], v[14:15], off
	v_readlane_b32 s5, v206, 7
	global_load_dwordx4 v[26:29], v[26:27], off
.LBB0_1255:
	s_waitcnt lgkmcnt(0)
	s_barrier
	ds_read_b128 v[156:159], v90 offset:24576
	ds_read_b128 v[160:163], v90 offset:24832
	ds_read_b128 v[168:171], v90 offset:25344
	ds_read_b32 v176, v103 offset:25856
	ds_read_b128 v[164:167], v90 offset:25088
	ds_read_b128 v[172:175], v90 offset:25600
	ds_read_b128 v[180:183], v90 offset:26112
	ds_read_b128 v[184:187], v90 offset:26368
	ds_read_b128 v[192:195], v90 offset:26880
	ds_read_b32 v178, v103 offset:27392
	ds_read_b128 v[188:191], v90 offset:26624
	ds_read_b128 v[196:199], v90 offset:27136
	ds_read_b128 v[52:55], v90 offset:27648
	ds_read_b128 v[56:59], v90 offset:27904
	ds_read_b128 v[64:67], v90 offset:28416
	ds_read_b32 v200, v103 offset:28928
	ds_read_b128 v[60:63], v90 offset:28160
	ds_read_b128 v[68:71], v90 offset:28672
	s_waitcnt lgkmcnt(12)
	v_pk_mul_f32 v[72:73], v[44:45], v[158:159]
	v_pk_mul_f32 v[74:75], v[42:43], v[160:161]
	v_pk_fma_f32 v[72:73], v[42:43], v[156:157], v[72:73]
	v_pk_mul_f32 v[76:77], v[44:45], v[162:163]
	v_add_f32_e32 v78, v72, v73
	v_pk_fma_f32 v[74:75], v[176:177], v[168:169], v[74:75] op_sel_hi:[0,1,1]
	v_pk_fma_f32 v[76:77], v[176:177], v[170:171], v[76:77] op_sel_hi:[0,1,1]
	v_add_f32_dpp v78, v78, v78 quad_perm:[1,0,3,2] row_mask:0xf bank_mask:0xf bound_ctrl:1
	ds_read_b128 v[210:213], v90 offset:29184
	ds_read_b128 v[214:217], v90 offset:29440
	v_add_f32_dpp v78, v78, v78 quad_perm:[2,3,0,1] row_mask:0xf bank_mask:0xf bound_ctrl:1
	ds_read_b128 v[222:225], v90 offset:29952
	ds_read_b32 v230, v103 offset:30464
	v_add_f32_dpp v78, v78, v78 row_half_mirror row_mask:0xf bank_mask:0xf bound_ctrl:1
	ds_read_b128 v[218:221], v90 offset:29696
	ds_read_b128 v[226:229], v90 offset:30208
	v_add_f32_dpp v78, v78, v78 row_mirror row_mask:0xf bank_mask:0xf bound_ctrl:1
	v_pk_fma_f32 v[44:45], v[166:167], v[78:79], v[76:77] op_sel_hi:[1,0,1]
	v_pk_fma_f32 v[42:43], v[164:165], v[78:79], v[74:75] op_sel_hi:[1,0,1]
	s_waitcnt lgkmcnt(12)
	v_pk_mul_f32 v[72:73], v[44:45], v[182:183]
	v_pk_mul_f32 v[80:81], v[44:45], v[174:175]
	v_pk_fma_f32 v[72:73], v[42:43], v[180:181], v[72:73]
	v_pk_fma_f32 v[80:81], v[42:43], v[172:173], v[80:81]
	v_add_f32_e32 v78, v72, v73
	v_add_f32_e32 v46, v80, v81
	v_pk_mul_f32 v[74:75], v[42:43], v[184:185]
	v_add_f32_dpp v78, v78, v78 quad_perm:[1,0,3,2] row_mask:0xf bank_mask:0xf bound_ctrl:1
	v_pk_mul_f32 v[76:77], v[44:45], v[186:187]
	v_pk_fma_f32 v[74:75], v[178:179], v[192:193], v[74:75] op_sel_hi:[0,1,1]
	v_add_f32_dpp v78, v78, v78 quad_perm:[2,3,0,1] row_mask:0xf bank_mask:0xf bound_ctrl:1
	v_pk_fma_f32 v[76:77], v[178:179], v[194:195], v[76:77] op_sel_hi:[0,1,1]
	ds_read_b128 v[156:159], v90 offset:30720
	v_add_f32_dpp v78, v78, v78 row_half_mirror row_mask:0xf bank_mask:0xf bound_ctrl:1
	ds_read_b128 v[160:163], v90 offset:30976
	ds_read_b128 v[168:171], v90 offset:31488
	v_add_f32_dpp v78, v78, v78 row_mirror row_mask:0xf bank_mask:0xf bound_ctrl:1
	v_pk_fma_f32 v[44:45], v[190:191], v[78:79], v[76:77] op_sel_hi:[1,0,1]
	v_pk_fma_f32 v[42:43], v[188:189], v[78:79], v[74:75] op_sel_hi:[1,0,1]
	ds_read_b32 v176, v103 offset:32000
	ds_read_b128 v[164:167], v90 offset:31232
	ds_read_b128 v[172:175], v90 offset:31744
	s_waitcnt lgkmcnt(12)
	v_pk_mul_f32 v[72:73], v[44:45], v[54:55]
	v_pk_mul_f32 v[80:81], v[44:45], v[198:199]
	v_pk_fma_f32 v[72:73], v[42:43], v[52:53], v[72:73]
	v_pk_fma_f32 v[80:81], v[42:43], v[196:197], v[80:81]
	v_add_f32_e32 v78, v72, v73
	v_add_f32_e32 v47, v80, v81
	v_pk_mul_f32 v[74:75], v[42:43], v[56:57]
	v_add_f32_dpp v78, v78, v78 quad_perm:[1,0,3,2] row_mask:0xf bank_mask:0xf bound_ctrl:1
	v_pk_mul_f32 v[76:77], v[44:45], v[58:59]
	v_pk_fma_f32 v[74:75], v[200:201], v[64:65], v[74:75] op_sel_hi:[0,1,1]
	v_add_f32_dpp v78, v78, v78 quad_perm:[2,3,0,1] row_mask:0xf bank_mask:0xf bound_ctrl:1
	v_pk_fma_f32 v[76:77], v[200:201], v[66:67], v[76:77] op_sel_hi:[0,1,1]
	ds_read_b128 v[180:183], v90 offset:32256
	v_add_f32_dpp v78, v78, v78 row_half_mirror row_mask:0xf bank_mask:0xf bound_ctrl:1
	ds_read_b128 v[184:187], v90 offset:32512
	ds_read_b128 v[192:195], v90 offset:33024
	v_add_f32_dpp v78, v78, v78 row_mirror row_mask:0xf bank_mask:0xf bound_ctrl:1
	v_pk_fma_f32 v[44:45], v[62:63], v[78:79], v[76:77] op_sel_hi:[1,0,1]
	v_pk_fma_f32 v[42:43], v[60:61], v[78:79], v[74:75] op_sel_hi:[1,0,1]
	ds_read_b32 v178, v103 offset:33536
	ds_read_b128 v[188:191], v90 offset:32768
	ds_read_b128 v[196:199], v90 offset:33280
	s_waitcnt lgkmcnt(12)
	v_pk_mul_f32 v[72:73], v[44:45], v[212:213]
	v_pk_mul_f32 v[80:81], v[44:45], v[70:71]
	v_pk_fma_f32 v[72:73], v[42:43], v[210:211], v[72:73]
	v_pk_fma_f32 v[80:81], v[42:43], v[68:69], v[80:81]
	v_add_f32_e32 v78, v72, v73
	v_add_f32_e32 v48, v80, v81
	v_pk_mul_f32 v[74:75], v[42:43], v[214:215]
	v_add_f32_dpp v78, v78, v78 quad_perm:[1,0,3,2] row_mask:0xf bank_mask:0xf bound_ctrl:1
	v_pk_mul_f32 v[76:77], v[44:45], v[216:217]
	v_pk_fma_f32 v[74:75], v[230:231], v[222:223], v[74:75] op_sel_hi:[0,1,1]
	v_add_f32_dpp v78, v78, v78 quad_perm:[2,3,0,1] row_mask:0xf bank_mask:0xf bound_ctrl:1
	v_pk_fma_f32 v[76:77], v[230:231], v[224:225], v[76:77] op_sel_hi:[0,1,1]
	ds_read_b128 v[52:55], v90 offset:33792
	v_add_f32_dpp v78, v78, v78 row_half_mirror row_mask:0xf bank_mask:0xf bound_ctrl:1
	ds_read_b128 v[56:59], v90 offset:34048
	ds_read_b128 v[64:67], v90 offset:34560
	v_add_f32_dpp v78, v78, v78 row_mirror row_mask:0xf bank_mask:0xf bound_ctrl:1
	v_pk_fma_f32 v[44:45], v[220:221], v[78:79], v[76:77] op_sel_hi:[1,0,1]
	v_pk_fma_f32 v[42:43], v[218:219], v[78:79], v[74:75] op_sel_hi:[1,0,1]
	ds_read_b32 v200, v103 offset:35072
	ds_read_b128 v[60:63], v90 offset:34304
	ds_read_b128 v[68:71], v90 offset:34816
	s_waitcnt lgkmcnt(12)
	v_pk_mul_f32 v[72:73], v[44:45], v[158:159]
	v_pk_mul_f32 v[80:81], v[44:45], v[228:229]
	v_pk_fma_f32 v[72:73], v[42:43], v[156:157], v[72:73]
	v_pk_fma_f32 v[80:81], v[42:43], v[226:227], v[80:81]
	v_add_f32_e32 v78, v72, v73
	v_add_f32_e32 v49, v80, v81
	v_pk_mul_f32 v[74:75], v[42:43], v[160:161]
	v_add_f32_dpp v78, v78, v78 quad_perm:[1,0,3,2] row_mask:0xf bank_mask:0xf bound_ctrl:1
	v_pk_mul_f32 v[76:77], v[44:45], v[162:163]
	v_pk_fma_f32 v[74:75], v[176:177], v[168:169], v[74:75] op_sel_hi:[0,1,1]
	v_add_f32_dpp v78, v78, v78 quad_perm:[2,3,0,1] row_mask:0xf bank_mask:0xf bound_ctrl:1
	v_pk_fma_f32 v[76:77], v[176:177], v[170:171], v[76:77] op_sel_hi:[0,1,1]
	ds_read_b128 v[210:213], v90 offset:35328
	v_add_f32_dpp v78, v78, v78 row_half_mirror row_mask:0xf bank_mask:0xf bound_ctrl:1
	ds_read_b128 v[214:217], v90 offset:35584
	ds_read_b128 v[222:225], v90 offset:36096
	v_add_f32_dpp v78, v78, v78 row_mirror row_mask:0xf bank_mask:0xf bound_ctrl:1
	v_pk_fma_f32 v[44:45], v[166:167], v[78:79], v[76:77] op_sel_hi:[1,0,1]
	v_pk_fma_f32 v[42:43], v[164:165], v[78:79], v[74:75] op_sel_hi:[1,0,1]
	ds_read_b32 v230, v103 offset:36608
	ds_read_b128 v[218:221], v90 offset:35840
	ds_read_b128 v[226:229], v90 offset:36352
	s_waitcnt lgkmcnt(12)
	v_pk_mul_f32 v[72:73], v[44:45], v[182:183]
	v_pk_mul_f32 v[80:81], v[44:45], v[174:175]
	v_pk_fma_f32 v[72:73], v[42:43], v[180:181], v[72:73]
	v_pk_fma_f32 v[80:81], v[42:43], v[172:173], v[80:81]
	v_add_f32_e32 v78, v72, v73
	v_add_f32_e32 v50, v80, v81
	v_pk_mul_f32 v[74:75], v[42:43], v[184:185]
	v_add_f32_dpp v78, v78, v78 quad_perm:[1,0,3,2] row_mask:0xf bank_mask:0xf bound_ctrl:1
	v_pk_mul_f32 v[76:77], v[44:45], v[186:187]
	v_pk_fma_f32 v[74:75], v[178:179], v[192:193], v[74:75] op_sel_hi:[0,1,1]
	v_add_f32_dpp v78, v78, v78 quad_perm:[2,3,0,1] row_mask:0xf bank_mask:0xf bound_ctrl:1
	v_pk_fma_f32 v[76:77], v[178:179], v[194:195], v[76:77] op_sel_hi:[0,1,1]
	ds_read_b128 v[156:159], v90 offset:36864
	v_add_f32_dpp v78, v78, v78 row_half_mirror row_mask:0xf bank_mask:0xf bound_ctrl:1
	ds_read_b128 v[160:163], v90 offset:37120
	ds_read_b128 v[168:171], v90 offset:37632
	v_add_f32_dpp v78, v78, v78 row_mirror row_mask:0xf bank_mask:0xf bound_ctrl:1
	v_pk_fma_f32 v[44:45], v[190:191], v[78:79], v[76:77] op_sel_hi:[1,0,1]
	v_pk_fma_f32 v[42:43], v[188:189], v[78:79], v[74:75] op_sel_hi:[1,0,1]
	ds_read_b32 v176, v103 offset:38144
	ds_read_b128 v[164:167], v90 offset:37376
	ds_read_b128 v[172:175], v90 offset:37888
	s_waitcnt lgkmcnt(12)
	v_pk_mul_f32 v[72:73], v[44:45], v[54:55]
	v_pk_mul_f32 v[80:81], v[44:45], v[198:199]
	v_pk_fma_f32 v[72:73], v[42:43], v[52:53], v[72:73]
	v_pk_fma_f32 v[80:81], v[42:43], v[196:197], v[80:81]
	v_add_f32_e32 v78, v72, v73
	v_add_f32_e32 v51, v80, v81
	v_pk_mul_f32 v[74:75], v[42:43], v[56:57]
	v_add_f32_dpp v78, v78, v78 quad_perm:[1,0,3,2] row_mask:0xf bank_mask:0xf bound_ctrl:1
	v_pk_mul_f32 v[76:77], v[44:45], v[58:59]
	v_pk_fma_f32 v[74:75], v[200:201], v[64:65], v[74:75] op_sel_hi:[0,1,1]
	v_add_f32_dpp v78, v78, v78 quad_perm:[2,3,0,1] row_mask:0xf bank_mask:0xf bound_ctrl:1
	v_pk_fma_f32 v[76:77], v[200:201], v[66:67], v[76:77] op_sel_hi:[0,1,1]
	ds_read_b128 v[180:183], v90 offset:38400
	v_add_f32_dpp v78, v78, v78 row_half_mirror row_mask:0xf bank_mask:0xf bound_ctrl:1
	ds_read_b128 v[184:187], v90 offset:38656
	ds_read_b128 v[192:195], v90 offset:39168
	v_add_f32_dpp v78, v78, v78 row_mirror row_mask:0xf bank_mask:0xf bound_ctrl:1
	v_pk_fma_f32 v[44:45], v[62:63], v[78:79], v[76:77] op_sel_hi:[1,0,1]
	v_pk_fma_f32 v[42:43], v[60:61], v[78:79], v[74:75] op_sel_hi:[1,0,1]
	ds_read_b32 v178, v103 offset:39680
	ds_read_b128 v[188:191], v90 offset:38912
	ds_read_b128 v[196:199], v90 offset:39424
	s_waitcnt lgkmcnt(12)
	v_pk_mul_f32 v[72:73], v[44:45], v[212:213]
	v_pk_mul_f32 v[80:81], v[44:45], v[70:71]
	v_pk_fma_f32 v[72:73], v[42:43], v[210:211], v[72:73]
	v_pk_fma_f32 v[80:81], v[42:43], v[68:69], v[80:81]
	v_add_f32_e32 v78, v72, v73
	v_add_f32_e32 v82, v80, v81
	v_pk_mul_f32 v[74:75], v[42:43], v[214:215]
	v_add_f32_dpp v78, v78, v78 quad_perm:[1,0,3,2] row_mask:0xf bank_mask:0xf bound_ctrl:1
	v_pk_mul_f32 v[76:77], v[44:45], v[216:217]
	v_pk_fma_f32 v[74:75], v[230:231], v[222:223], v[74:75] op_sel_hi:[0,1,1]
	v_add_f32_dpp v78, v78, v78 quad_perm:[2,3,0,1] row_mask:0xf bank_mask:0xf bound_ctrl:1
	v_pk_fma_f32 v[76:77], v[230:231], v[224:225], v[76:77] op_sel_hi:[0,1,1]
	ds_read_b128 v[52:55], v90 offset:39936
	v_add_f32_dpp v78, v78, v78 row_half_mirror row_mask:0xf bank_mask:0xf bound_ctrl:1
	ds_read_b128 v[56:59], v90 offset:40192
	ds_read_b128 v[64:67], v90 offset:40704
	v_add_f32_dpp v78, v78, v78 row_mirror row_mask:0xf bank_mask:0xf bound_ctrl:1
	v_pk_fma_f32 v[44:45], v[220:221], v[78:79], v[76:77] op_sel_hi:[1,0,1]
	v_pk_fma_f32 v[42:43], v[218:219], v[78:79], v[74:75] op_sel_hi:[1,0,1]
	ds_read_b32 v200, v103 offset:41216
	ds_read_b128 v[60:63], v90 offset:40448
	ds_read_b128 v[68:71], v90 offset:40960
	s_waitcnt lgkmcnt(12)
	v_pk_mul_f32 v[72:73], v[44:45], v[158:159]
	v_pk_mul_f32 v[80:81], v[44:45], v[228:229]
	v_pk_fma_f32 v[72:73], v[42:43], v[156:157], v[72:73]
	v_pk_fma_f32 v[80:81], v[42:43], v[226:227], v[80:81]
	v_add_f32_e32 v78, v72, v73
	v_add_f32_e32 v83, v80, v81
	v_pk_mul_f32 v[74:75], v[42:43], v[160:161]
	v_add_f32_dpp v78, v78, v78 quad_perm:[1,0,3,2] row_mask:0xf bank_mask:0xf bound_ctrl:1
	v_pk_mul_f32 v[76:77], v[44:45], v[162:163]
	v_pk_fma_f32 v[74:75], v[176:177], v[168:169], v[74:75] op_sel_hi:[0,1,1]
	v_add_f32_dpp v78, v78, v78 quad_perm:[2,3,0,1] row_mask:0xf bank_mask:0xf bound_ctrl:1
	v_pk_fma_f32 v[76:77], v[176:177], v[170:171], v[76:77] op_sel_hi:[0,1,1]
	ds_read_b128 v[210:213], v90 offset:41472
	v_add_f32_dpp v78, v78, v78 row_half_mirror row_mask:0xf bank_mask:0xf bound_ctrl:1
	ds_read_b128 v[214:217], v90 offset:41728
	ds_read_b128 v[222:225], v90 offset:42240
	v_add_f32_dpp v78, v78, v78 row_mirror row_mask:0xf bank_mask:0xf bound_ctrl:1
	v_pk_fma_f32 v[44:45], v[166:167], v[78:79], v[76:77] op_sel_hi:[1,0,1]
	v_pk_fma_f32 v[42:43], v[164:165], v[78:79], v[74:75] op_sel_hi:[1,0,1]
	ds_read_b32 v230, v103 offset:42752
	ds_read_b128 v[218:221], v90 offset:41984
	ds_read_b128 v[226:229], v90 offset:42496
	s_waitcnt lgkmcnt(12)
	v_pk_mul_f32 v[72:73], v[44:45], v[182:183]
	v_pk_mul_f32 v[80:81], v[44:45], v[174:175]
	v_pk_fma_f32 v[72:73], v[42:43], v[180:181], v[72:73]
	v_pk_fma_f32 v[80:81], v[42:43], v[172:173], v[80:81]
	v_add_f32_e32 v78, v72, v73
	v_add_f32_e32 v84, v80, v81
	v_pk_mul_f32 v[74:75], v[42:43], v[184:185]
	v_add_f32_dpp v78, v78, v78 quad_perm:[1,0,3,2] row_mask:0xf bank_mask:0xf bound_ctrl:1
	v_pk_mul_f32 v[76:77], v[44:45], v[186:187]
	v_pk_fma_f32 v[74:75], v[178:179], v[192:193], v[74:75] op_sel_hi:[0,1,1]
	v_add_f32_dpp v78, v78, v78 quad_perm:[2,3,0,1] row_mask:0xf bank_mask:0xf bound_ctrl:1
	v_pk_fma_f32 v[76:77], v[178:179], v[194:195], v[76:77] op_sel_hi:[0,1,1]
	ds_read_b128 v[156:159], v90 offset:43008
	v_add_f32_dpp v78, v78, v78 row_half_mirror row_mask:0xf bank_mask:0xf bound_ctrl:1
	ds_read_b128 v[160:163], v90 offset:43264
	ds_read_b128 v[168:171], v90 offset:43776
	v_add_f32_dpp v78, v78, v78 row_mirror row_mask:0xf bank_mask:0xf bound_ctrl:1
	v_pk_fma_f32 v[44:45], v[190:191], v[78:79], v[76:77] op_sel_hi:[1,0,1]
	v_pk_fma_f32 v[42:43], v[188:189], v[78:79], v[74:75] op_sel_hi:[1,0,1]
	ds_read_b32 v176, v103 offset:44288
	ds_read_b128 v[164:167], v90 offset:43520
	ds_read_b128 v[172:175], v90 offset:44032
	s_waitcnt lgkmcnt(12)
	v_pk_mul_f32 v[72:73], v[44:45], v[54:55]
	v_pk_mul_f32 v[80:81], v[44:45], v[198:199]
	v_pk_fma_f32 v[72:73], v[42:43], v[52:53], v[72:73]
	v_pk_fma_f32 v[80:81], v[42:43], v[196:197], v[80:81]
	v_add_f32_e32 v78, v72, v73
	v_add_f32_e32 v85, v80, v81
	v_pk_mul_f32 v[74:75], v[42:43], v[56:57]
	v_add_f32_dpp v78, v78, v78 quad_perm:[1,0,3,2] row_mask:0xf bank_mask:0xf bound_ctrl:1
	v_pk_mul_f32 v[76:77], v[44:45], v[58:59]
	v_pk_fma_f32 v[74:75], v[200:201], v[64:65], v[74:75] op_sel_hi:[0,1,1]
	v_add_f32_dpp v78, v78, v78 quad_perm:[2,3,0,1] row_mask:0xf bank_mask:0xf bound_ctrl:1
	v_pk_fma_f32 v[76:77], v[200:201], v[66:67], v[76:77] op_sel_hi:[0,1,1]
	ds_read_b128 v[180:183], v90 offset:44544
	v_add_f32_dpp v78, v78, v78 row_half_mirror row_mask:0xf bank_mask:0xf bound_ctrl:1
	ds_read_b128 v[184:187], v90 offset:44800
	ds_read_b128 v[192:195], v90 offset:45312
	v_add_f32_dpp v78, v78, v78 row_mirror row_mask:0xf bank_mask:0xf bound_ctrl:1
	v_pk_fma_f32 v[44:45], v[62:63], v[78:79], v[76:77] op_sel_hi:[1,0,1]
	v_pk_fma_f32 v[42:43], v[60:61], v[78:79], v[74:75] op_sel_hi:[1,0,1]
	ds_read_b32 v178, v103 offset:45824
	ds_read_b128 v[188:191], v90 offset:45056
	ds_read_b128 v[196:199], v90 offset:45568
	s_waitcnt lgkmcnt(12)
	v_pk_mul_f32 v[72:73], v[44:45], v[212:213]
	v_pk_mul_f32 v[80:81], v[44:45], v[70:71]
	v_pk_fma_f32 v[72:73], v[42:43], v[210:211], v[72:73]
	v_pk_fma_f32 v[80:81], v[42:43], v[68:69], v[80:81]
	v_add_f32_e32 v78, v72, v73
	v_add_f32_e32 v100, v80, v81
	v_pk_mul_f32 v[74:75], v[42:43], v[214:215]
	v_add_f32_dpp v78, v78, v78 quad_perm:[1,0,3,2] row_mask:0xf bank_mask:0xf bound_ctrl:1
	v_pk_mul_f32 v[76:77], v[44:45], v[216:217]
	v_pk_fma_f32 v[74:75], v[230:231], v[222:223], v[74:75] op_sel_hi:[0,1,1]
	v_add_f32_dpp v78, v78, v78 quad_perm:[2,3,0,1] row_mask:0xf bank_mask:0xf bound_ctrl:1
	v_pk_fma_f32 v[76:77], v[230:231], v[224:225], v[76:77] op_sel_hi:[0,1,1]
	ds_read_b128 v[52:55], v90 offset:46080
	v_add_f32_dpp v78, v78, v78 row_half_mirror row_mask:0xf bank_mask:0xf bound_ctrl:1
	ds_read_b128 v[56:59], v90 offset:46336
	ds_read_b128 v[64:67], v90 offset:46848
	v_add_f32_dpp v78, v78, v78 row_mirror row_mask:0xf bank_mask:0xf bound_ctrl:1
	v_pk_fma_f32 v[44:45], v[220:221], v[78:79], v[76:77] op_sel_hi:[1,0,1]
	v_pk_fma_f32 v[42:43], v[218:219], v[78:79], v[74:75] op_sel_hi:[1,0,1]
	ds_read_b32 v200, v103 offset:47360
	ds_read_b128 v[60:63], v90 offset:46592
	ds_read_b128 v[68:71], v90 offset:47104
	s_waitcnt lgkmcnt(12)
	v_pk_mul_f32 v[72:73], v[44:45], v[158:159]
	v_pk_mul_f32 v[80:81], v[44:45], v[228:229]
	v_pk_fma_f32 v[72:73], v[42:43], v[156:157], v[72:73]
	v_pk_fma_f32 v[80:81], v[42:43], v[226:227], v[80:81]
	v_add_f32_e32 v78, v72, v73
	v_add_f32_e32 v101, v80, v81
	v_pk_mul_f32 v[74:75], v[42:43], v[160:161]
	v_add_f32_dpp v78, v78, v78 quad_perm:[1,0,3,2] row_mask:0xf bank_mask:0xf bound_ctrl:1
	v_pk_mul_f32 v[76:77], v[44:45], v[162:163]
	v_pk_fma_f32 v[74:75], v[176:177], v[168:169], v[74:75] op_sel_hi:[0,1,1]
	v_add_f32_dpp v78, v78, v78 quad_perm:[2,3,0,1] row_mask:0xf bank_mask:0xf bound_ctrl:1
	v_pk_fma_f32 v[76:77], v[176:177], v[170:171], v[76:77] op_sel_hi:[0,1,1]
	ds_read_b128 v[210:213], v90 offset:47616
	v_add_f32_dpp v78, v78, v78 row_half_mirror row_mask:0xf bank_mask:0xf bound_ctrl:1
	ds_read_b128 v[214:217], v90 offset:47872
	ds_read_b128 v[222:225], v90 offset:48384
	v_add_f32_dpp v78, v78, v78 row_mirror row_mask:0xf bank_mask:0xf bound_ctrl:1
	v_pk_fma_f32 v[44:45], v[166:167], v[78:79], v[76:77] op_sel_hi:[1,0,1]
	v_pk_fma_f32 v[42:43], v[164:165], v[78:79], v[74:75] op_sel_hi:[1,0,1]
	ds_read_b32 v230, v103 offset:48896
	ds_read_b128 v[218:221], v90 offset:48128
	ds_read_b128 v[226:229], v90 offset:48640
	s_waitcnt lgkmcnt(12)
	v_pk_mul_f32 v[72:73], v[44:45], v[182:183]
	v_pk_mul_f32 v[80:81], v[44:45], v[174:175]
	v_pk_fma_f32 v[72:73], v[42:43], v[180:181], v[72:73]
	v_pk_fma_f32 v[80:81], v[42:43], v[172:173], v[80:81]
	v_add_f32_e32 v78, v72, v73
	v_add_f32_e32 v102, v80, v81
	v_pk_mul_f32 v[74:75], v[42:43], v[184:185]
	v_add_f32_dpp v78, v78, v78 quad_perm:[1,0,3,2] row_mask:0xf bank_mask:0xf bound_ctrl:1
	v_pk_mul_f32 v[76:77], v[44:45], v[186:187]
	v_pk_fma_f32 v[74:75], v[178:179], v[192:193], v[74:75] op_sel_hi:[0,1,1]
	v_add_f32_dpp v78, v78, v78 quad_perm:[2,3,0,1] row_mask:0xf bank_mask:0xf bound_ctrl:1
	v_pk_fma_f32 v[76:77], v[178:179], v[194:195], v[76:77] op_sel_hi:[0,1,1]
	s_nop 0
	v_add_f32_dpp v78, v78, v78 row_half_mirror row_mask:0xf bank_mask:0xf bound_ctrl:1
	s_nop 0
	s_nop 0
	v_add_f32_dpp v78, v78, v78 row_mirror row_mask:0xf bank_mask:0xf bound_ctrl:1
	v_pk_fma_f32 v[44:45], v[190:191], v[78:79], v[76:77] op_sel_hi:[1,0,1]
	v_pk_fma_f32 v[42:43], v[188:189], v[78:79], v[74:75] op_sel_hi:[1,0,1]
	s_waitcnt lgkmcnt(6)
	v_pk_mul_f32 v[72:73], v[44:45], v[54:55]
	v_pk_mul_f32 v[80:81], v[44:45], v[198:199]
	v_pk_fma_f32 v[72:73], v[42:43], v[52:53], v[72:73]
	v_pk_fma_f32 v[80:81], v[42:43], v[196:197], v[80:81]
	v_add_f32_e32 v78, v72, v73
	v_add_f32_e32 v104, v80, v81
	v_pk_mul_f32 v[74:75], v[42:43], v[56:57]
	v_add_f32_dpp v78, v78, v78 quad_perm:[1,0,3,2] row_mask:0xf bank_mask:0xf bound_ctrl:1
	v_pk_mul_f32 v[76:77], v[44:45], v[58:59]
	v_pk_fma_f32 v[74:75], v[200:201], v[64:65], v[74:75] op_sel_hi:[0,1,1]
	v_add_f32_dpp v78, v78, v78 quad_perm:[2,3,0,1] row_mask:0xf bank_mask:0xf bound_ctrl:1
	v_pk_fma_f32 v[76:77], v[200:201], v[66:67], v[76:77] op_sel_hi:[0,1,1]
	s_nop 0
	v_add_f32_dpp v78, v78, v78 row_half_mirror row_mask:0xf bank_mask:0xf bound_ctrl:1
	s_nop 0
	s_nop 0
	v_add_f32_dpp v78, v78, v78 row_mirror row_mask:0xf bank_mask:0xf bound_ctrl:1
	v_pk_fma_f32 v[44:45], v[62:63], v[78:79], v[76:77] op_sel_hi:[1,0,1]
	v_pk_fma_f32 v[42:43], v[60:61], v[78:79], v[74:75] op_sel_hi:[1,0,1]
	s_waitcnt lgkmcnt(0)
	v_pk_mul_f32 v[72:73], v[44:45], v[212:213]
	v_pk_mul_f32 v[80:81], v[44:45], v[70:71]
	v_pk_fma_f32 v[72:73], v[42:43], v[210:211], v[72:73]
	v_pk_fma_f32 v[80:81], v[42:43], v[68:69], v[80:81]
	v_add_f32_e32 v78, v72, v73
	v_add_f32_e32 v108, v80, v81
	v_pk_mul_f32 v[74:75], v[42:43], v[214:215]
	v_add_f32_dpp v78, v78, v78 quad_perm:[1,0,3,2] row_mask:0xf bank_mask:0xf bound_ctrl:1
	v_pk_mul_f32 v[76:77], v[44:45], v[216:217]
	v_pk_fma_f32 v[74:75], v[230:231], v[222:223], v[74:75] op_sel_hi:[0,1,1]
	v_add_f32_dpp v78, v78, v78 quad_perm:[2,3,0,1] row_mask:0xf bank_mask:0xf bound_ctrl:1
	v_pk_fma_f32 v[76:77], v[230:231], v[224:225], v[76:77] op_sel_hi:[0,1,1]
	s_nop 0
	v_add_f32_dpp v78, v78, v78 row_half_mirror row_mask:0xf bank_mask:0xf bound_ctrl:1
	s_nop 0
	s_nop 0
	v_add_f32_dpp v78, v78, v78 row_mirror row_mask:0xf bank_mask:0xf bound_ctrl:1
	v_pk_fma_f32 v[44:45], v[220:221], v[78:79], v[76:77] op_sel_hi:[1,0,1]
	v_pk_fma_f32 v[42:43], v[218:219], v[78:79], v[74:75] op_sel_hi:[1,0,1]
	s_mov_b32 s4, 0xcccccccc
	v_pk_mul_f32 v[80:81], v[44:45], v[228:229]
	s_mov_b32 s5, 0xcccccccc
	v_pk_fma_f32 v[80:81], v[42:43], v[226:227], v[80:81]
	s_mov_b32 s12, 0xaaaaaaaa
	s_mov_b32 s13, 0xaaaaaaaa
	v_add_f32_e32 v177, v80, v81
	v_add_f32_dpp v46, v46, v46 row_ror:8 row_mask:0xf bank_mask:0x3
	v_add_f32_dpp v47, v47, v47 row_ror:8 row_mask:0xf bank_mask:0x3
	v_add_f32_dpp v48, v48, v48 row_ror:8 row_mask:0xf bank_mask:0x3
	v_add_f32_dpp v49, v49, v49 row_ror:8 row_mask:0xf bank_mask:0x3
	v_add_f32_dpp v50, v50, v50 row_ror:8 row_mask:0xf bank_mask:0x3
	v_add_f32_dpp v51, v51, v51 row_ror:8 row_mask:0xf bank_mask:0x3
	v_add_f32_dpp v82, v82, v82 row_ror:8 row_mask:0xf bank_mask:0x3
	v_add_f32_dpp v83, v83, v83 row_ror:8 row_mask:0xf bank_mask:0x3
	v_add_f32_dpp v46, v84, v84 row_ror:8 row_mask:0xf bank_mask:0xc
	v_add_f32_dpp v47, v85, v85 row_ror:8 row_mask:0xf bank_mask:0xc
	v_add_f32_dpp v48, v100, v100 row_ror:8 row_mask:0xf bank_mask:0xc
	v_add_f32_dpp v49, v101, v101 row_ror:8 row_mask:0xf bank_mask:0xc
	v_add_f32_dpp v50, v102, v102 row_ror:8 row_mask:0xf bank_mask:0xc
	v_add_f32_dpp v51, v104, v104 row_ror:8 row_mask:0xf bank_mask:0xc
	v_add_f32_dpp v82, v108, v108 row_ror:8 row_mask:0xf bank_mask:0xc
	v_add_f32_dpp v83, v177, v177 row_ror:8 row_mask:0xf bank_mask:0xc
	v_add_f32_dpp v46, v46, v46 row_shl:4 row_mask:0xf bank_mask:0x5
	v_add_f32_dpp v47, v47, v47 row_shl:4 row_mask:0xf bank_mask:0x5
	v_add_f32_dpp v48, v48, v48 row_shl:4 row_mask:0xf bank_mask:0x5
	v_add_f32_dpp v49, v49, v49 row_shl:4 row_mask:0xf bank_mask:0x5
	v_add_f32_dpp v46, v50, v50 row_shr:4 row_mask:0xf bank_mask:0xa
	v_add_f32_dpp v47, v51, v51 row_shr:4 row_mask:0xf bank_mask:0xa
	v_add_f32_dpp v48, v82, v82 row_shr:4 row_mask:0xf bank_mask:0xa
	v_add_f32_dpp v49, v83, v83 row_shr:4 row_mask:0xf bank_mask:0xa
	v_add_f32_dpp v84, v46, v46 quad_perm:[2,3,0,1] row_mask:0xf bank_mask:0xf
	v_add_f32_dpp v85, v47, v47 quad_perm:[2,3,0,1] row_mask:0xf bank_mask:0xf
	v_add_f32_dpp v100, v48, v48 quad_perm:[2,3,0,1] row_mask:0xf bank_mask:0xf
	v_add_f32_dpp v101, v49, v49 quad_perm:[2,3,0,1] row_mask:0xf bank_mask:0xf
	v_cndmask_b32_e64 v50, v84, v100, s[4:5]
	v_cndmask_b32_e64 v51, v85, v101, s[4:5]
	s_nop 0
	v_add_f32_dpp v82, v50, v50 quad_perm:[1,0,3,2] row_mask:0xf bank_mask:0xf
	v_add_f32_dpp v83, v51, v51 quad_perm:[1,0,3,2] row_mask:0xf bank_mask:0xf
	v_cndmask_b32_e64 v48, v82, v83, s[12:13]
	v_lshl_or_b32 v156, s7, 4, v87
	v_xor_b32_e32 v49, 0xffffffef, v156
	v_add_u32_e32 v49, s18, v49
	s_add_i32 s10, s7, 2
	v_or_b32_e32 v46, 16, v156
	v_cndmask_b32_e64 v46, v49, v46, s[16:17]
	s_cmp_ge_u32 s10, s19
	v_ashrrev_i32_e32 v47, 31, v46
	v_lshlrev_b64 v[46:47], 10, v[46:47]
	s_cselect_b64 s[2:3], -1, 0
	v_lshl_add_u64 v[46:47], v[98:99], 0, v[46:47]
	s_and_b64 vcc, exec, s[2:3]
	global_store_dword v[46:47], v48, off
	s_cbranch_vccnz .LBB0_1259
	s_waitcnt vmcnt(2)
	v_lshlrev_b32_e32 v46, 16, v38
	v_and_b32_e32 v47, 0xffff0000, v38
	v_lshlrev_b32_e32 v48, 16, v39
	v_and_b32_e32 v49, 0xffff0000, v39
	ds_write_b128 v96, v[18:21]
	ds_write_b128 v96, v[22:25] offset:6144
	ds_write_b128 v96, v[30:33] offset:12288
	ds_write_b128 v96, v[34:37] offset:18432
	ds_write_b128 v97, v[46:49] offset:1024
	v_lshlrev_b32_e32 v46, 16, v40
	v_and_b32_e32 v47, 0xffff0000, v40
	v_lshlrev_b32_e32 v48, 16, v41
	v_and_b32_e32 v49, 0xffff0000, v41
	ds_write_b128 v97, v[46:49] offset:1040

	.amdhsa_kernel _Z14fwd_megakernel6Params
		.amdhsa_group_segment_fixed_size 49168
		.amdhsa_private_segment_fixed_size 0
		.amdhsa_kernarg_size 840
		.amdhsa_user_sgpr_count 2
		.amdhsa_user_sgpr_dispatch_ptr 0
		.amdhsa_user_sgpr_queue_ptr 0
		.amdhsa_user_sgpr_kernarg_segment_ptr 1
		.amdhsa_user_sgpr_dispatch_id 0
		.amdhsa_user_sgpr_kernarg_preload_length 0
		.amdhsa_user_sgpr_kernarg_preload_offset 0
		.amdhsa_user_sgpr_private_segment_size 0
		.amdhsa_uses_dynamic_stack 0
		.amdhsa_enable_private_segment 0
		.amdhsa_system_sgpr_workgroup_id_x 1
		.amdhsa_system_sgpr_workgroup_id_y 0
		.amdhsa_system_sgpr_workgroup_id_z 0
		.amdhsa_system_sgpr_workgroup_info 0
		.amdhsa_system_vgpr_workitem_id 0
		.amdhsa_next_free_vgpr 232
		.amdhsa_next_free_sgpr 100
		.amdhsa_accum_offset 232
		.amdhsa_reserve_vcc 1
		.amdhsa_float_round_mode_32 0
		.amdhsa_float_round_mode_16_64 0
		.amdhsa_float_denorm_mode_32 3
		.amdhsa_float_denorm_mode_16_64 3
		.amdhsa_dx10_clamp 1
		.amdhsa_ieee_mode 1
		.amdhsa_fp16_overflow 0
		.amdhsa_tg_split 0
		.amdhsa_exception_fp_ieee_invalid_op 0
		.amdhsa_exception_fp_denorm_src 0
		.amdhsa_exception_fp_ieee_div_zero 0
		.amdhsa_exception_fp_ieee_overflow 0
		.amdhsa_exception_fp_ieee_underflow 0
		.amdhsa_exception_fp_ieee_inexact 0
		.amdhsa_exception_int_div_zero 0
	.end_amdhsa_kernel

amdhsa.kernels:
  - .agpr_count:     0
    .args:
      - .offset:         0
        .size:           584
        .value_kind:     by_value
      - .offset:         584
        .size:           4
        .value_kind:     hidden_block_count_x
      - .offset:         588
        .size:           4
        .value_kind:     hidden_block_count_y
      - .offset:         592
        .size:           4
        .value_kind:     hidden_block_count_z
      - .offset:         596
        .size:           2
        .value_kind:     hidden_group_size_x
      - .offset:         598
        .size:           2
        .value_kind:     hidden_group_size_y
      - .offset:         600
        .size:           2
        .value_kind:     hidden_group_size_z
      - .offset:         602
        .size:           2
        .value_kind:     hidden_remainder_x
      - .offset:         604
        .size:           2
        .value_kind:     hidden_remainder_y
      - .offset:         606
        .size:           2
        .value_kind:     hidden_remainder_z
      - .offset:         624
        .size:           8
        .value_kind:     hidden_global_offset_x
      - .offset:         632
        .size:           8
        .value_kind:     hidden_global_offset_y
      - .offset:         640
        .size:           8
        .value_kind:     hidden_global_offset_z
      - .offset:         648
        .size:           2
        .value_kind:     hidden_grid_dims
    .group_segment_fixed_size: 49168
    .kernarg_segment_align: 8
    .kernarg_segment_size: 840
    .language:       OpenCL C
    .language_version:
      - 2
      - 0
    .max_flat_workgroup_size: 256
    .name:           _Z14fwd_megakernel6Params
    .private_segment_fixed_size: 0
    .sgpr_count:     106
    .sgpr_spill_count: 452
    .symbol:         _Z14fwd_megakernel6Params.kd
    .uniform_work_group_size: 1
    .uses_dynamic_stack: false
    .vgpr_count:     232
    .vgpr_spill_count: 0
    .wavefront_size: 64
